# HGRN2 phases A and C: chunk cumsum with its LDS round trips batched (8 reads up front, prefix in registers, segment offsets read in one round trip, wave-uniform scalar exits); same additions in the sa
# baseline (speedup 1.0000x reference)
; #define LAS __attribute__((address_space(3)))
; __device__ __forceinline__ void unpack8(u32x4 w, float* v) { v[0] = bflo(w.x); v[1] = bfhi(w.x); v[2] = bflo(w.y); v[3] = bfhi(w.y); v[4] = bflo(w.z); v[5] = bfhi(w.z); v[6] = bflo(w.w); v[7] = bfhi(w.w); }
; __device__ __forceinline__ void unit_a_pre(LAS float* sm, int u, const PreA& pre, const float* lbt0, float* STB, float* HD, int tid) {
;     const int lane = tid & 63, w = __builtin_amdgcn_readfirstlane(tid >> 6); const int chunk = u & 255, dir = (u >> 8) & 1, h = (u >> 9) & 3, b = u >> 11;
;     { const int tl = tid >> 3, c8 = (tid & 7) * 8, j = dir ? 63 - tl : tl; const float* lbt = lbt0 + dir * 256;
;       const f32x4 l0 = *(const f32x4*)(lbt + h * 64 + c8), l1 = *(const f32x4*)(lbt + h * 64 + c8 + 4);
;       const float z[8] = {pre.z0[0], pre.z0[1], pre.z0[2], pre.z0[3], pre.z1[0], pre.z1[1], pre.z1[2], pre.z1[3]}, lb[8] = {l0[0], l0[1], l0[2], l0[3], l1[0], l1[1], l1[2], l1[3]};
;       float v[8]; unpack8(pre.v, v);
; #pragma unroll
;       for (int e = 0; e < 8; ++e) { const float sg = __builtin_amdgcn_rcpf(1.f + __expf(-z[e])); const float f = lb[e] + (1.f - lb[e]) * sg;
;           sm[O_B + j * ST + c8 + e] = __logf(f); sm[O_K + j * ST + c8 + e] = (1.f - lb[e]) * __builtin_amdgcn_rcpf(1.f + __expf(z[e])); sm[O_V + j * 64 + c8 + e] = v[e]; } }
.LBB0_809:
	s_bfe_u32 s69, s65, 0x10008
	s_bfe_u32 s52, s65, 0x20009
	s_cmp_eq_u32 s69, 0
	s_cselect_b64 vcc, -1, 0
	s_lshl_b32 s2, s69, 10
	s_add_u32 s2, s1, s2
	s_addc_u32 s9, s28, 0
	s_lshl_b32 s8, s52, 8
	s_add_u32 s8, s2, s8
	s_addc_u32 s9, s9, 0
	global_load_dwordx4 v[16:19], v178, s[8:9] offset:16
	global_load_dwordx4 v[24:27], v178, s[8:9]
	v_lshlrev_b32_e32 v50, 16, v30
	v_and_b32_e32 v49, 0xffff0000, v30
	v_lshlrev_b32_e32 v39, 16, v31
	v_and_b32_e32 v30, 0xffff0000, v31
	v_mul_f32_e32 v31, 0xbfb8aa3b, v20
	v_exp_f32_e32 v31, v31
	v_cndmask_b32_e32 v52, v40, v33, vcc
	v_lshlrev_b32_e32 v53, 16, v28
	v_and_b32_e32 v54, 0xffff0000, v28
	v_add_f32_e32 v31, 1.0, v31
	v_rcp_f32_e32 v31, v31
	v_lshlrev_b32_e32 v55, 16, v29
	v_and_b32_e32 v51, 0xffff0000, v29
	v_mad_u64_u32 v[28:29], s[8:9], v52, s3, v[36:37]
	v_lshl_add_u32 v29, v52, 8, 0
	v_mul_f32_e32 v20, 0x3fb8aa3b, v20
	v_exp_f32_e32 v20, v20
	s_mov_b32 s2, 0x16580
	v_add3_u32 v29, v29, v178, s2
	v_readfirstlane_b32 s68, v37
	v_add_f32_e32 v20, 1.0, v20
	v_rcp_f32_e32 v20, v20
	s_waitcnt vmcnt(0)
	v_sub_f32_e32 v52, 1.0, v24
	v_fma_f32 v24, v31, v52, v24
	v_cmp_gt_f32_e64 s[8:9], s33, v24
	v_mul_f32_e32 v20, v20, v52
	s_nop 0
	v_cndmask_b32_e64 v31, 0, 32, s[8:9]
	v_ldexp_f32 v24, v24, v31
	v_log_f32_e32 v24, v24
	v_cndmask_b32_e64 v56, 0, v224, s[8:9]
	v_mul_f32_e32 v31, 0x3f317217, v24
	v_fma_f32 v31, v24, s30, -v31
	v_fmac_f32_e32 v31, 0x3377d1cf, v24
	v_fmac_f32_e32 v31, 0x3f317217, v24
	v_cmp_lt_f32_e64 s[10:11], |v24|, s31
	s_nop 1
	v_cndmask_b32_e64 v31, v24, v31, s[10:11]
	v_sub_f32_e32 v31, v31, v56
	ds_write_b32 v28, v31 offset:33280
	ds_write_b32 v28, v20 offset:16640
	ds_write_b32 v29, v53
	v_mul_f32_e32 v20, 0xbfb8aa3b, v21
	v_exp_f32_e32 v20, v20
	v_sub_f32_e32 v31, 1.0, v25
	v_mov_b32_e32 v24, 0
	v_add_f32_e32 v20, 1.0, v20
	v_rcp_f32_e32 v20, v20
	s_nop 0
	v_fma_f32 v20, v20, v31, v25
	v_cmp_gt_f32_e64 s[8:9], s33, v20
	s_nop 1
	v_cndmask_b32_e64 v25, 0, 32, s[8:9]
	v_ldexp_f32 v20, v20, v25
	v_log_f32_e32 v20, v20
	s_nop 0
	v_mul_f32_e32 v25, 0x3f317217, v20
	v_fma_f32 v25, v20, s30, -v25
	v_fmac_f32_e32 v25, 0x3377d1cf, v20
	v_fmac_f32_e32 v25, 0x3f317217, v20
	v_cmp_lt_f32_e64 s[10:11], |v20|, s31
	s_nop 1
	v_cndmask_b32_e64 v20, v20, v25, s[10:11]
	v_cndmask_b32_e64 v25, 0, v224, s[8:9]
	v_sub_f32_e32 v20, v20, v25
	ds_write_b32 v28, v20 offset:33284
	v_mul_f32_e32 v20, 0x3fb8aa3b, v21
	v_exp_f32_e32 v20, v20
	v_sub_f32_e32 v21, 1.0, v26
	v_add_f32_e32 v20, 1.0, v20
	v_rcp_f32_e32 v20, v20
	s_nop 0
	v_mul_f32_e32 v20, v20, v31
	ds_write_b32 v28, v20 offset:16644
	ds_write_b32 v29, v54 offset:4
	v_mul_f32_e32 v20, 0xbfb8aa3b, v22
	v_exp_f32_e32 v20, v20
	s_nop 0
	v_add_f32_e32 v20, 1.0, v20
	v_rcp_f32_e32 v20, v20
	s_nop 0
	v_fma_f32 v20, v20, v21, v26
	v_cmp_gt_f32_e64 s[8:9], s33, v20
	s_nop 1
	v_cndmask_b32_e64 v25, 0, 32, s[8:9]
	v_ldexp_f32 v20, v20, v25
	v_log_f32_e32 v20, v20
	s_nop 0
	v_mul_f32_e32 v25, 0x3f317217, v20
	v_fma_f32 v25, v20, s30, -v25
	v_fmac_f32_e32 v25, 0x3377d1cf, v20
	v_fmac_f32_e32 v25, 0x3f317217, v20
	v_cmp_lt_f32_e64 s[10:11], |v20|, s31
	s_nop 1
	v_cndmask_b32_e64 v20, v20, v25, s[10:11]
	v_cndmask_b32_e64 v25, 0, v224, s[8:9]
	v_sub_f32_e32 v20, v20, v25
	ds_write_b32 v28, v20 offset:33288
	v_mul_f32_e32 v20, 0x3fb8aa3b, v22
	v_exp_f32_e32 v20, v20
	s_nop 0
	v_add_f32_e32 v20, 1.0, v20
	v_rcp_f32_e32 v20, v20
	s_nop 0
	v_mul_f32_e32 v20, v20, v21
	ds_write_b32 v28, v20 offset:16648
	ds_write_b32 v29, v55 offset:8
	v_mul_f32_e32 v20, 0xbfb8aa3b, v23
	v_exp_f32_e32 v20, v20
	v_sub_f32_e32 v21, 1.0, v27
	v_add_f32_e32 v20, 1.0, v20
	v_rcp_f32_e32 v20, v20
	s_nop 0
	v_fmac_f32_e32 v27, v20, v21
	v_cmp_gt_f32_e64 s[8:9], s33, v27
	s_nop 1
	v_cndmask_b32_e64 v20, 0, 32, s[8:9]
	v_ldexp_f32 v20, v27, v20
	v_log_f32_e32 v20, v20
	s_nop 0
	v_mul_f32_e32 v22, 0x3f317217, v20
	v_fma_f32 v22, v20, s30, -v22
	v_fmac_f32_e32 v22, 0x3377d1cf, v20
	v_fmac_f32_e32 v22, 0x3f317217, v20
	v_cmp_lt_f32_e64 s[10:11], |v20|, s31
	s_nop 1
	v_cndmask_b32_e64 v20, v20, v22, s[10:11]
	v_cndmask_b32_e64 v22, 0, v224, s[8:9]
	v_sub_f32_e32 v20, v20, v22
	ds_write_b32 v28, v20 offset:33292
	v_mul_f32_e32 v20, 0x3fb8aa3b, v23
	v_exp_f32_e32 v20, v20
	s_nop 0
	v_add_f32_e32 v20, 1.0, v20
	v_rcp_f32_e32 v20, v20
	s_nop 0
	v_mul_f32_e32 v20, v20, v21
	ds_write_b32 v28, v20 offset:16652
	ds_write_b32 v29, v51 offset:12
	v_mul_f32_e32 v20, 0xbfb8aa3b, v12
	v_exp_f32_e32 v20, v20
	v_sub_f32_e32 v21, 1.0, v16
	v_mul_f32_e32 v12, 0x3fb8aa3b, v12
	v_exp_f32_e32 v12, v12
	v_add_f32_e32 v20, 1.0, v20
	v_rcp_f32_e32 v20, v20
	v_add_f32_e32 v12, 1.0, v12
	v_rcp_f32_e32 v12, v12
	v_fma_f32 v16, v20, v21, v16
	v_cmp_gt_f32_e64 s[8:9], s33, v16
	v_mul_f32_e32 v12, v12, v21
	s_nop 0
	v_cndmask_b32_e64 v20, 0, 32, s[8:9]
	v_ldexp_f32 v16, v16, v20
	v_log_f32_e32 v16, v16
	s_nop 0
	v_mul_f32_e32 v20, 0x3f317217, v16
	v_fma_f32 v20, v16, s30, -v20
	v_fmac_f32_e32 v20, 0x3377d1cf, v16
	v_fmac_f32_e32 v20, 0x3f317217, v16
	v_cmp_lt_f32_e64 s[10:11], |v16|, s31
	s_nop 1
	v_cndmask_b32_e64 v16, v16, v20, s[10:11]
	v_cndmask_b32_e64 v20, 0, v224, s[8:9]
	v_sub_f32_e32 v16, v16, v20
	ds_write_b32 v28, v16 offset:33296
	ds_write_b32 v28, v12 offset:16656
	ds_write_b32 v29, v50 offset:16
	v_mul_f32_e32 v12, 0xbfb8aa3b, v13
	v_exp_f32_e32 v12, v12
	v_sub_f32_e32 v16, 1.0, v17
	v_add_f32_e32 v12, 1.0, v12
	v_rcp_f32_e32 v12, v12
	s_nop 0
	v_fma_f32 v12, v12, v16, v17
	v_cmp_gt_f32_e64 s[8:9], s33, v12
	s_nop 1
	v_cndmask_b32_e64 v17, 0, 32, s[8:9]
	v_ldexp_f32 v12, v12, v17
	v_log_f32_e32 v12, v12
	s_nop 0
	v_mul_f32_e32 v17, 0x3f317217, v12
	v_fma_f32 v17, v12, s30, -v17
; #define LAS __attribute__((address_space(3)))
; __device__ __forceinline__ void cumsum_b(LAS float* sm, int tid) {
;     const int d = tid & 63, seg = tid >> 6; float run = 0.f;
; #pragma unroll
;     for (int r = 0; r < 8; ++r) { const int ix = O_B + (seg * 8 + r) * ST + d; run += sm[ix]; sm[ix] = run; }
;     sm[O_TMP + seg * 64 + d] = run;
;     __syncthreads();
;     float off = 0.f;
;     for (int s = 0; s < seg; ++s) off += sm[O_TMP + s * 64 + d];
; __device__ __forceinline__ void unit_a_pre(LAS float* sm, int u, const PreA& pre, const float* lbt0, float* STB, float* HD, int tid) {
;     ...
;       for (int e = 0; e < 8; ++e) { const float sg = __builtin_amdgcn_rcpf(1.f + __expf(-z[e])); const float f = lb[e] + (1.f - lb[e]) * sg;
;           sm[O_B + j * ST + c8 + e] = __logf(f); sm[O_K + j * ST + c8 + e] = (1.f - lb[e]) * __builtin_amdgcn_rcpf(1.f + __expf(z[e])); sm[O_V + j * 64 + c8 + e] = v[e]; } }
	v_fmac_f32_e32 v17, 0x3377d1cf, v12
	v_fmac_f32_e32 v17, 0x3f317217, v12
	v_cmp_lt_f32_e64 s[10:11], |v12|, s31
	s_nop 1
	v_cndmask_b32_e64 v12, v12, v17, s[10:11]
	v_cndmask_b32_e64 v17, 0, v224, s[8:9]
	v_sub_f32_e32 v12, v12, v17
	ds_write_b32 v28, v12 offset:33300
	v_mul_f32_e32 v12, 0x3fb8aa3b, v13
	v_exp_f32_e32 v12, v12
	v_sub_f32_e32 v13, 1.0, v18
	v_add_f32_e32 v12, 1.0, v12
	v_rcp_f32_e32 v12, v12
	s_nop 0
	v_mul_f32_e32 v12, v12, v16
	ds_write_b32 v28, v12 offset:16660
	ds_write_b32 v29, v49 offset:20
	v_mul_f32_e32 v12, 0xbfb8aa3b, v14
	v_exp_f32_e32 v12, v12
	s_nop 0
	v_add_f32_e32 v12, 1.0, v12
	v_rcp_f32_e32 v12, v12
	s_nop 0
	v_fma_f32 v12, v12, v13, v18
	v_cmp_gt_f32_e64 s[8:9], s33, v12
	s_nop 1
	v_cndmask_b32_e64 v16, 0, 32, s[8:9]
	v_ldexp_f32 v12, v12, v16
	v_log_f32_e32 v12, v12
	s_nop 0
	v_mul_f32_e32 v16, 0x3f317217, v12
	v_fma_f32 v16, v12, s30, -v16
	v_fmac_f32_e32 v16, 0x3377d1cf, v12
	v_fmac_f32_e32 v16, 0x3f317217, v12
	v_cmp_lt_f32_e64 s[10:11], |v12|, s31
	s_nop 1
	v_cndmask_b32_e64 v12, v12, v16, s[10:11]
	v_cndmask_b32_e64 v16, 0, v224, s[8:9]
	v_sub_f32_e32 v12, v12, v16
	ds_write_b32 v28, v12 offset:33304
	v_mul_f32_e32 v12, 0x3fb8aa3b, v14
	v_exp_f32_e32 v12, v12
	s_nop 0
	v_add_f32_e32 v12, 1.0, v12
	v_rcp_f32_e32 v12, v12
	s_nop 0
	v_mul_f32_e32 v12, v12, v13
	ds_write_b32 v28, v12 offset:16664
	ds_write_b32 v29, v39 offset:24
	v_mul_f32_e32 v12, 0xbfb8aa3b, v15
	v_exp_f32_e32 v12, v12
	v_sub_f32_e32 v13, 1.0, v19
	v_add_f32_e32 v12, 1.0, v12
	v_rcp_f32_e32 v12, v12
	s_nop 0
	v_fmac_f32_e32 v19, v12, v13
	v_cmp_gt_f32_e64 s[8:9], s33, v19
	s_nop 1
	v_cndmask_b32_e64 v12, 0, 32, s[8:9]
	v_ldexp_f32 v12, v19, v12
	v_log_f32_e32 v12, v12
	s_nop 0
	v_mul_f32_e32 v14, 0x3f317217, v12
	v_fma_f32 v14, v12, s30, -v14
	v_fmac_f32_e32 v14, 0x3377d1cf, v12
	v_fmac_f32_e32 v14, 0x3f317217, v12
	v_cmp_lt_f32_e64 s[10:11], |v12|, s31
	s_nop 1
	v_cndmask_b32_e64 v12, v12, v14, s[10:11]
	v_cndmask_b32_e64 v14, 0, v224, s[8:9]
	v_sub_f32_e32 v12, v12, v14
	ds_write_b32 v28, v12 offset:33308
	v_mul_f32_e32 v12, 0x3fb8aa3b, v15
	v_exp_f32_e32 v12, v12
	v_add_u32_e32 v14, 0x8000, v42
	v_add_f32_e32 v12, 1.0, v12
	v_rcp_f32_e32 v12, v12
	s_nop 0
	v_mul_f32_e32 v12, v12, v13
	ds_write_b32 v28, v12 offset:16668
	ds_write_b32 v29, v30 offset:28
	s_waitcnt lgkmcnt(0)
	s_barrier
	ds_read_b32 v60, v42 offset:33280
	ds_read_b32 v61, v42 offset:33540
	ds_read_b32 v62, v42 offset:33800
	ds_read_b32 v63, v42 offset:34060
	ds_read_b32 v64, v42 offset:34320
	ds_read_b32 v65, v42 offset:34580
	ds_read_b32 v66, v42 offset:34840
	ds_read_b32 v67, v42 offset:35100
	v_readfirstlane_b32 s24, v37
	s_waitcnt lgkmcnt(7)
	v_add_f32_e32 v60, 0, v60
	s_waitcnt lgkmcnt(6)
	v_add_f32_e32 v61, v60, v61
	s_waitcnt lgkmcnt(5)
	v_add_f32_e32 v62, v61, v62
	s_waitcnt lgkmcnt(4)
	v_add_f32_e32 v63, v62, v63
	s_waitcnt lgkmcnt(3)
	v_add_f32_e32 v64, v63, v64
	s_waitcnt lgkmcnt(2)
	v_add_f32_e32 v65, v64, v65
	s_waitcnt lgkmcnt(1)
	v_add_f32_e32 v66, v65, v66
	s_waitcnt lgkmcnt(0)
	v_add_f32_e32 v67, v66, v67
	ds_write_b32 v42, v60 offset:33280
	ds_write_b32 v42, v61 offset:33540
	ds_write_b32 v42, v62 offset:33800
	ds_write_b32 v42, v63 offset:34060
	ds_write_b32 v42, v64 offset:34320
	ds_write_b32 v42, v65 offset:34580
	ds_write_b32 v42, v66 offset:34840
	ds_write_b32 v42, v67 offset:35100
	ds_write_b32 v43, v67
	s_waitcnt lgkmcnt(0)
	s_barrier
	ds_read_b32 v68, v46
	ds_read_b32 v69, v46 offset:256
	ds_read_b32 v70, v46 offset:512
	ds_read_b32 v71, v46 offset:768
	ds_read_b32 v72, v46 offset:1024
	ds_read_b32 v73, v46 offset:1280
	ds_read_b32 v74, v46 offset:1536
	v_mov_b32_e32 v75, 0
	s_waitcnt lgkmcnt(0)
	s_cmp_eq_u32 s24, 0
	s_cbranch_scc1 .Lhga_csdone
	v_add_f32_e32 v75, v75, v68
	s_cmp_eq_u32 s24, 1
	s_cbranch_scc1 .Lhga_csdone
	v_add_f32_e32 v75, v75, v69
	s_cmp_eq_u32 s24, 2
	s_cbranch_scc1 .Lhga_csdone
	v_add_f32_e32 v75, v75, v70
	s_cmp_eq_u32 s24, 3
	s_cbranch_scc1 .Lhga_csdone
	v_add_f32_e32 v75, v75, v71
	s_cmp_eq_u32 s24, 4
	s_cbranch_scc1 .Lhga_csdone
	v_add_f32_e32 v75, v75, v72
	s_cmp_eq_u32 s24, 5
	s_cbranch_scc1 .Lhga_csdone
	v_add_f32_e32 v75, v75, v73
	s_cmp_eq_u32 s24, 6
	s_cbranch_scc1 .Lhga_csdone
	v_add_f32_e32 v75, v75, v74
; __device__ __forceinline__ void cumsum_b(LAS float* sm, int tid) {
;     ...
;     float off = 0.f;
;     for (int s = 0; s < seg; ++s) off += sm[O_TMP + s * 64 + d];
; #pragma unroll
;     for (int r = 0; r < 8; ++r) sm[O_B + (seg * 8 + r) * ST + d] += off;
;     __syncthreads();
; __device__ __forceinline__ void unit_a_pre(LAS float* sm, int u, const PreA& pre, const float* lbt0, float* STB, float* HD, int tid) {
;     ...
;     { const int d = tid & 63, seg = tid >> 6; const float bl = sm[O_B + 63 * ST + d];
; #pragma unroll
;       for (int r = 0; r < 8; ++r) { const int ix = (seg * 8 + r) * ST + d; sm[O_K + ix] *= __expf(bl - sm[O_B + ix]); } }
;     __syncthreads();
.Lhga_csdone:
	v_add_f32_e32 v60, v75, v60
	v_add_f32_e32 v61, v75, v61
	v_add_f32_e32 v62, v75, v62
	v_add_f32_e32 v63, v75, v63
	v_add_f32_e32 v64, v75, v64
	v_add_f32_e32 v65, v75, v65
	v_add_f32_e32 v66, v75, v66
	v_add_f32_e32 v67, v75, v67
	ds_write_b32 v42, v60 offset:33280
	ds_write_b32 v42, v61 offset:33540
	ds_write_b32 v42, v62 offset:33800
	ds_write_b32 v42, v63 offset:34060
	ds_write_b32 v42, v64 offset:34320
	ds_write_b32 v42, v65 offset:34580
	ds_write_b32 v42, v66 offset:34840
	ds_write_b32 v42, v67 offset:35100
	v_add_u32_e32 v13, 0x8400, v42
	v_add_u32_e32 v12, 0x8800, v42
	v_add_u32_e32 v19, 0x4000, v42
	s_lshl_b32 s8, s68, 1
	s_ashr_i32 s11, s68, 1
	s_and_b32 s10, s8, 2
	s_lshl_b32 s2, s69, 8
	s_mov_b32 s8, -4
	s_waitcnt lgkmcnt(0)
	s_barrier
	ds_read_b32 v18, v41 offset:49660
	ds_read2_b32 v[14:15], v14 offset0:128 offset1:193
	ds_read2_b32 v[16:17], v19 offset0:64 offset1:129
	s_waitcnt lgkmcnt(1)
	v_sub_f32_e32 v14, v18, v14
	v_sub_f32_e32 v15, v18, v15
	v_mul_f32_e32 v14, 0x3fb8aa3b, v14
	v_mul_f32_e32 v15, 0x3fb8aa3b, v15
	v_exp_f32_e32 v14, v14
	v_exp_f32_e32 v15, v15
	s_waitcnt lgkmcnt(0)
	v_mul_f32_e32 v14, v16, v14
	v_mul_f32_e32 v15, v17, v15
	ds_write2_b32 v19, v14, v15 offset0:64 offset1:129
	ds_read2_b32 v[14:15], v13 offset0:2 offset1:67
	v_add_u32_e32 v19, 0x4200, v42
	ds_read2_b32 v[16:17], v19 offset0:66 offset1:131
	s_waitcnt lgkmcnt(1)
	v_sub_f32_e32 v14, v18, v14
	v_sub_f32_e32 v15, v18, v15
	v_mul_f32_e32 v14, 0x3fb8aa3b, v14
	v_mul_f32_e32 v15, 0x3fb8aa3b, v15
	v_exp_f32_e32 v14, v14
	v_exp_f32_e32 v15, v15
	s_waitcnt lgkmcnt(0)
	v_mul_f32_e32 v14, v16, v14
	v_mul_f32_e32 v15, v17, v15
	ds_write2_b32 v19, v14, v15 offset0:66 offset1:131
	ds_read2_b32 v[14:15], v13 offset0:132 offset1:197
	v_lshl_add_u32 v19, s11, 6, v48
	s_waitcnt lgkmcnt(0)
	v_sub_f32_e32 v13, v18, v14
	v_add_u32_e32 v14, 0x4400, v42
	v_sub_f32_e32 v15, v18, v15
	v_mul_f32_e32 v13, 0x3fb8aa3b, v13
	ds_read2_b32 v[16:17], v14 offset0:68 offset1:133
	v_mul_f32_e32 v15, 0x3fb8aa3b, v15
	v_exp_f32_e32 v13, v13
	v_exp_f32_e32 v15, v15
	s_waitcnt lgkmcnt(0)
	v_mul_f32_e32 v13, v16, v13
	v_mul_f32_e32 v15, v17, v15
	ds_write2_b32 v14, v13, v15 offset0:68 offset1:133
	ds_read2_b32 v[12:13], v12 offset0:6 offset1:71
	v_add_u32_e32 v16, 0x4600, v42
	ds_read2_b32 v[14:15], v16 offset0:70 offset1:135
	s_waitcnt lgkmcnt(1)
	v_sub_f32_e32 v12, v18, v12
	v_sub_f32_e32 v13, v18, v13
	v_mul_f32_e32 v12, 0x3fb8aa3b, v12
	v_mul_f32_e32 v13, 0x3fb8aa3b, v13
	v_exp_f32_e32 v12, v12
	v_exp_f32_e32 v13, v13
	v_lshl_add_u32 v18, s10, 6, v47
	v_mov_b32_e32 v17, v18
	s_waitcnt lgkmcnt(0)
	v_mul_f32_e32 v12, v14, v12
	v_mul_f32_e32 v13, v15, v13
	ds_write2_b32 v16, v12, v13 offset0:70 offset1:135
	v_mov_b32_e32 v12, 0
	v_mov_b32_e32 v16, v19
	v_mov_b32_e32 v13, v12
	v_mov_b32_e32 v14, v12
	v_mov_b32_e32 v15, v12
	s_waitcnt lgkmcnt(0)
	s_barrier

; #define LAS __attribute__((address_space(3)))
; __device__ __forceinline__ void cumsum_b(LAS float* sm, int tid) {
;     const int d = tid & 63, seg = tid >> 6; float run = 0.f;
; #pragma unroll
;     for (int r = 0; r < 8; ++r) { const int ix = O_B + (seg * 8 + r) * ST + d; run += sm[ix]; sm[ix] = run; }
;     sm[O_TMP + seg * 64 + d] = run;
;     __syncthreads();
;     float off = 0.f;
;     for (int s = 0; s < seg; ++s) off += sm[O_TMP + s * 64 + d];
; #pragma unroll
;     for (int r = 0; r < 8; ++r) sm[O_B + (seg * 8 + r) * ST + d] += off;
;     __syncthreads();
; __device__ __forceinline__ void phase_c(LAS float* sm, int bx, int G, const float* ZF0, const float* ZF1, const bf16_t* HQ, const bf16_t* HI, const bf16_t* HGs, const float* lbt, const float* STB,
;                                         const float* normg, bf16_t* MIX) {
;     ...
;         { const int d = tid & 63, seg = tid >> 6, I = seg >> 1;
;           float rj[4]; rj[0] = 0.f; rj[1] = sm[O_B + 15 * ST + d]; rj[2] = sm[O_B + 31 * ST + d]; rj[3] = sm[O_B + 47 * ST + d];
; #pragma unroll
;           for (int r = 0; r < 8; ++r) { const int ix = (seg * 8 + r) * ST + d; const float bt = sm[O_B + ix], q = sm[O_Q + ix], k = sm[O_K + ix];
;               sm[O_QB + ix] = q * __expf(bt);
;               sm[O_Q + ix] = q * __expf(bt - (I == 0 ? rj[0] : I == 1 ? rj[1] : I == 2 ? rj[2] : rj[3]));
; #pragma unroll
;               for (int J = 0; J < 4; ++J) if (J >= I) sm[ksbase(J) + ix] = k * __expf(fminf(rj[J] - bt, 80.f)); } }
.LBB0_1086:
	v_add_u32_e32 v27, 0x8000, v50
	s_waitcnt lgkmcnt(0)
	s_barrier
	ds_read_b32 v156, v50 offset:33280
	ds_read_b32 v157, v50 offset:33540
	ds_read_b32 v158, v50 offset:33800
	ds_read_b32 v159, v50 offset:34060
	ds_read_b32 v160, v50 offset:34320
	ds_read_b32 v161, v50 offset:34580
	ds_read_b32 v162, v50 offset:34840
	ds_read_b32 v163, v50 offset:35100
	v_readfirstlane_b32 s22, v33
	s_waitcnt lgkmcnt(7)
	v_add_f32_e32 v156, 0, v156
	s_waitcnt lgkmcnt(6)
	v_add_f32_e32 v157, v156, v157
	s_waitcnt lgkmcnt(5)
	v_add_f32_e32 v158, v157, v158
	s_waitcnt lgkmcnt(4)
	v_add_f32_e32 v159, v158, v159
	s_waitcnt lgkmcnt(3)
	v_add_f32_e32 v160, v159, v160
	s_waitcnt lgkmcnt(2)
	v_add_f32_e32 v161, v160, v161
	s_waitcnt lgkmcnt(1)
	v_add_f32_e32 v162, v161, v162
	s_waitcnt lgkmcnt(0)
	v_add_f32_e32 v163, v162, v163
	ds_write_b32 v50, v156 offset:33280
	ds_write_b32 v50, v157 offset:33540
	ds_write_b32 v50, v158 offset:33800
	ds_write_b32 v50, v159 offset:34060
	ds_write_b32 v50, v160 offset:34320
	ds_write_b32 v50, v161 offset:34580
	ds_write_b32 v50, v162 offset:34840
	ds_write_b32 v50, v163 offset:35100
	ds_write_b32 v51, v163
	s_waitcnt lgkmcnt(0)
	s_barrier
	ds_read_b32 v164, v111
	ds_read_b32 v165, v111 offset:256
	ds_read_b32 v166, v111 offset:512
	ds_read_b32 v167, v111 offset:768
	ds_read_b32 v168, v111 offset:1024
	ds_read_b32 v169, v111 offset:1280
	ds_read_b32 v170, v111 offset:1536
	v_mov_b32_e32 v171, 0
	s_waitcnt lgkmcnt(0)
	s_cmp_eq_u32 s22, 0
	s_cbranch_scc1 .Lhgc_csdone
	v_add_f32_e32 v171, v171, v164
	s_cmp_eq_u32 s22, 1
	s_cbranch_scc1 .Lhgc_csdone
	v_add_f32_e32 v171, v171, v165
	s_cmp_eq_u32 s22, 2
	s_cbranch_scc1 .Lhgc_csdone
	v_add_f32_e32 v171, v171, v166
	s_cmp_eq_u32 s22, 3
	s_cbranch_scc1 .Lhgc_csdone
	v_add_f32_e32 v171, v171, v167
	s_cmp_eq_u32 s22, 4
	s_cbranch_scc1 .Lhgc_csdone
	v_add_f32_e32 v171, v171, v168
	s_cmp_eq_u32 s22, 5
	s_cbranch_scc1 .Lhgc_csdone
	v_add_f32_e32 v171, v171, v169
	s_cmp_eq_u32 s22, 6
	s_cbranch_scc1 .Lhgc_csdone
	v_add_f32_e32 v171, v171, v170
.Lhgc_csdone:
	v_add_f32_e32 v156, v171, v156
	v_add_f32_e32 v157, v171, v157
	v_add_f32_e32 v158, v171, v158
	v_add_f32_e32 v159, v171, v159
	v_add_f32_e32 v160, v171, v160
	v_add_f32_e32 v161, v171, v161
	v_add_f32_e32 v162, v171, v162
	v_add_f32_e32 v163, v171, v163
	ds_write_b32 v50, v156 offset:33280
	ds_write_b32 v50, v157 offset:33540
	ds_write_b32 v50, v158 offset:33800
	ds_write_b32 v50, v159 offset:34060
	ds_write_b32 v50, v160 offset:34320
	ds_write_b32 v50, v161 offset:34580
	ds_write_b32 v50, v162 offset:34840
	ds_write_b32 v50, v163 offset:35100
	s_waitcnt lgkmcnt(0)
	s_barrier
	ds_read_b32 v28, v48 offset:37180
	ds_read_b32 v27, v48 offset:41340
	ds_read_b32 v26, v48 offset:45500
	s_waitcnt lgkmcnt(0)
	v_cndmask_b32_e64 v24, v26, v27, s[10:11]
	v_cndmask_b32_e64 v24, v24, v28, s[8:9]
	v_cndmask_b32_e64 v29, v24, 0, s[6:7]
	ds_read_b32 v30, v50 offset:33280
	ds_read2st64_b32 v[24:25], v50 offset1:65
	s_waitcnt lgkmcnt(1)
	v_sub_f32_e32 v53, v30, v29
	v_mul_f32_e32 v31, 0x3fb8aa3b, v30
	v_mul_f32_e32 v53, 0x3fb8aa3b, v53
	v_exp_f32_e32 v31, v31
	v_exp_f32_e32 v53, v53
	s_waitcnt lgkmcnt(0)
	v_mul_f32_e32 v31, v24, v31
	v_mul_f32_e32 v24, v24, v53
	ds_write2st64_b32 v50, v24, v31 offset1:195
	s_and_saveexec_b64 s[22:23], s[12:13]
	s_cbranch_execz .LBB0_1094
	v_min_f32_e64 v24, -v30, s67
	v_mul_f32_e32 v24, 0x3fb8aa3b, v24
	v_exp_f32_e32 v24, v24
	s_nop 0
	v_mul_f32_e32 v24, v25, v24
	ds_write_b32 v87, v24
	s_or_b64 exec, exec, s[22:23]
	s_and_saveexec_b64 s[22:23], s[14:15]
	s_cbranch_execnz .LBB0_1095
